# adds: attention P.V section straight-line per item kind with V^T fragment reads 8 deep in flight (counted lgkmcnt), no per-MFMA branch
# baseline (speedup 1.0000x reference)
.LBB0_1417:
	s_and_b64 vcc, exec, s[76:77]
	s_cbranch_vccnz .Lpv_one_tile
	v_add_u32_e32 v50, s88, v142
	s_movk_i32 s0, 0x150
	v_mad_u32_u24 v52, v206, s0, v50
	v_add_u32_e32 v52, 0x5800, v52
	ds_read2_b64 v[220:223], v52 offset0:64 offset1:68
	v_mul_u32_u24_e32 v52, 0x150, v206
	v_add_u32_e32 v50, v52, v50
	v_add_u32_e32 v143, 0x6800, v50
	ds_read2_b64 v[224:227], v143 offset0:224 offset1:228
	v_add_u32_e32 v52, 0x8000, v50
	ds_read2_b64 v[228:231], v52 offset0:128 offset1:132
	v_add_u32_e32 v53, 0x9800, v50
	ds_read2_b64 v[232:235], v53 offset0:32 offset1:36
	v_add_u32_e32 v144, 0x5800, v50
	ds_read2_b64 v[236:239], v144 offset0:72 offset1:76
	ds_read2_b64 v[240:243], v143 offset0:232 offset1:236
	ds_read2_b64 v[244:247], v52 offset0:136 offset1:140
	ds_read2_b64 v[248:251], v53 offset0:40 offset1:44
	s_waitcnt lgkmcnt(7)
	s_mov_b32 s86, s84
	s_mov_b32 s87, s84
	s_mov_b32 s85, s84
	v_mov_b64_e32 v[112:113], s[86:87]
	v_mov_b64_e32 v[110:111], s[84:85]
	v_mfma_f32_16x16x32_bf16 v[126:129], v[220:223], v[86:89], 0
	v_mfma_f32_16x16x32_bf16 v[110:113], v[220:223], v[106:109], 0
	ds_read2_b64 v[220:223], v144 offset0:80 offset1:84
	s_waitcnt lgkmcnt(7)
	v_mov_b64_e32 v[116:117], s[86:87]
	v_mov_b64_e32 v[114:115], s[84:85]
	v_mfma_f32_16x16x32_bf16 v[130:133], v[224:227], v[86:89], 0
	v_mfma_f32_16x16x32_bf16 v[114:117], v[224:227], v[106:109], 0
	ds_read2_b64 v[224:227], v143 offset0:240 offset1:244
	s_waitcnt lgkmcnt(7)
	s_mov_b32 s86, s84
	s_mov_b32 s87, s84
	s_mov_b32 s85, s84
	v_mov_b64_e32 v[120:121], s[86:87]
	v_mov_b64_e32 v[118:119], s[84:85]
	v_mfma_f32_16x16x32_bf16 v[134:137], v[228:231], v[86:89], 0
	v_mfma_f32_16x16x32_bf16 v[118:121], v[228:231], v[106:109], 0
	ds_read2_b64 v[228:231], v52 offset0:144 offset1:148
	s_waitcnt lgkmcnt(7)
	v_mov_b64_e32 v[124:125], s[86:87]
	v_mov_b64_e32 v[122:123], s[84:85]
	v_mfma_f32_16x16x32_bf16 v[86:89], v[232:235], v[86:89], 0
	v_mfma_f32_16x16x32_bf16 v[122:125], v[232:235], v[106:109], 0
	ds_read2_b64 v[232:235], v53 offset0:48 offset1:52
	s_waitcnt lgkmcnt(7)
	v_readlane_b32 s85, v253, 30
	v_mfma_f32_16x16x32_bf16 v[106:109], v[236:239], v[82:85], v[126:129]
	v_mfma_f32_16x16x32_bf16 v[110:113], v[236:239], v[102:105], v[110:113]
	ds_read2_b64 v[236:239], v144 offset0:88 offset1:92
	s_waitcnt lgkmcnt(7)
	v_mfma_f32_16x16x32_bf16 v[126:129], v[240:243], v[82:85], v[130:133]
	v_mfma_f32_16x16x32_bf16 v[114:117], v[240:243], v[102:105], v[114:117]
	ds_read2_b64 v[240:243], v143 offset0:248 offset1:252
	s_waitcnt lgkmcnt(7)
	v_mfma_f32_16x16x32_bf16 v[130:133], v[244:247], v[82:85], v[134:137]
	v_mfma_f32_16x16x32_bf16 v[118:121], v[244:247], v[102:105], v[118:121]
	ds_read2_b64 v[244:247], v52 offset0:152 offset1:156
	s_waitcnt lgkmcnt(7)
	v_mfma_f32_16x16x32_bf16 v[82:85], v[248:251], v[82:85], v[86:89]
	v_mfma_f32_16x16x32_bf16 v[122:125], v[248:251], v[102:105], v[122:125]
	ds_read2_b64 v[248:251], v53 offset0:56 offset1:60
	s_waitcnt lgkmcnt(7)
	v_mfma_f32_16x16x32_bf16 v[86:89], v[220:223], v[78:81], v[106:109]
	v_mfma_f32_16x16x32_bf16 v[110:113], v[220:223], v[98:101], v[110:113]
	ds_read2_b64 v[220:223], v144 offset0:96 offset1:100
	s_waitcnt lgkmcnt(7)
	v_mfma_f32_16x16x32_bf16 v[102:105], v[224:227], v[78:81], v[126:129]
	v_mfma_f32_16x16x32_bf16 v[114:117], v[224:227], v[98:101], v[114:117]
	v_add_u32_e32 v50, 0x7000, v50
	ds_read2_b64 v[224:227], v50 offset1:4
	s_waitcnt lgkmcnt(7)
	v_mfma_f32_16x16x32_bf16 v[106:109], v[228:231], v[78:81], v[130:133]
	v_mfma_f32_16x16x32_bf16 v[118:121], v[228:231], v[98:101], v[118:121]
	ds_read2_b64 v[228:231], v52 offset0:160 offset1:164
	s_waitcnt lgkmcnt(7)
	v_mfma_f32_16x16x32_bf16 v[126:129], v[232:235], v[78:81], v[82:85]
	v_mfma_f32_16x16x32_bf16 v[122:125], v[232:235], v[98:101], v[122:125]
	ds_read2_b64 v[232:235], v53 offset0:64 offset1:68
	s_waitcnt lgkmcnt(7)
	v_mfma_f32_16x16x32_bf16 v[86:89], v[236:239], v[74:77], v[86:89]
	v_mfma_f32_16x16x32_bf16 v[110:113], v[236:239], v[94:97], v[110:113]
	s_waitcnt lgkmcnt(6)
	v_mfma_f32_16x16x32_bf16 v[78:81], v[240:243], v[74:77], v[102:105]
	v_mfma_f32_16x16x32_bf16 v[114:117], v[240:243], v[94:97], v[114:117]
	s_waitcnt lgkmcnt(5)
	v_mfma_f32_16x16x32_bf16 v[82:85], v[244:247], v[74:77], v[106:109]
	v_mfma_f32_16x16x32_bf16 v[118:121], v[244:247], v[94:97], v[118:121]
	s_waitcnt lgkmcnt(4)
	v_mfma_f32_16x16x32_bf16 v[74:77], v[248:251], v[74:77], v[126:129]
	v_mfma_f32_16x16x32_bf16 v[122:125], v[248:251], v[94:97], v[122:125]
	s_waitcnt lgkmcnt(3)
	v_mfma_f32_16x16x32_bf16 v[86:89], v[220:223], v[70:73], v[86:89]
	v_mfma_f32_16x16x32_bf16 v[110:113], v[220:223], v[90:93], v[110:113]
	s_waitcnt lgkmcnt(2)
	v_mfma_f32_16x16x32_bf16 v[78:81], v[224:227], v[70:73], v[78:81]
	v_mfma_f32_16x16x32_bf16 v[114:117], v[224:227], v[90:93], v[114:117]
	s_waitcnt lgkmcnt(1)
	v_mfma_f32_16x16x32_bf16 v[82:85], v[228:231], v[70:73], v[82:85]
	v_mfma_f32_16x16x32_bf16 v[118:121], v[228:231], v[90:93], v[118:121]
	s_waitcnt lgkmcnt(0)
	v_mfma_f32_16x16x32_bf16 v[70:73], v[232:235], v[70:73], v[74:77]
	v_mfma_f32_16x16x32_bf16 v[122:125], v[232:235], v[90:93], v[122:125]
	s_and_b64 vcc, exec, s[76:77]
	s_branch .LBB0_1457
.Lpv_one_tile:
	v_add_u32_e32 v50, s88, v142
	s_movk_i32 s0, 0x150
	v_mad_u32_u24 v52, v206, s0, v50
	v_add_u32_e32 v52, 0x5800, v52
	ds_read2_b64 v[220:223], v52 offset0:64 offset1:68
	v_mul_u32_u24_e32 v52, 0x150, v206
	v_add_u32_e32 v50, v52, v50
	v_add_u32_e32 v143, 0x6800, v50
	ds_read2_b64 v[224:227], v143 offset0:224 offset1:228
	v_add_u32_e32 v52, 0x8000, v50
	ds_read2_b64 v[228:231], v52 offset0:128 offset1:132
	v_add_u32_e32 v53, 0x9800, v50
	ds_read2_b64 v[232:235], v53 offset0:32 offset1:36
	v_add_u32_e32 v144, 0x5800, v50
	ds_read2_b64 v[236:239], v144 offset0:72 offset1:76
	ds_read2_b64 v[240:243], v143 offset0:232 offset1:236
	ds_read2_b64 v[244:247], v52 offset0:136 offset1:140
	ds_read2_b64 v[248:251], v53 offset0:40 offset1:44
	s_waitcnt lgkmcnt(7)
	s_mov_b32 s86, s84
	s_mov_b32 s87, s84
	s_mov_b32 s85, s84
	v_mov_b64_e32 v[112:113], s[86:87]
	v_mov_b64_e32 v[110:111], s[84:85]
	v_mfma_f32_16x16x32_bf16 v[126:129], v[220:223], v[86:89], 0
	ds_read2_b64 v[220:223], v144 offset0:80 offset1:84
	s_waitcnt lgkmcnt(7)
	v_mov_b64_e32 v[116:117], s[86:87]
	v_mov_b64_e32 v[114:115], s[84:85]
	v_mfma_f32_16x16x32_bf16 v[130:133], v[224:227], v[86:89], 0
	ds_read2_b64 v[224:227], v143 offset0:240 offset1:244
	s_waitcnt lgkmcnt(7)
	s_mov_b32 s86, s84
	s_mov_b32 s87, s84
	s_mov_b32 s85, s84
	v_mov_b64_e32 v[120:121], s[86:87]
	v_mov_b64_e32 v[118:119], s[84:85]
	v_mfma_f32_16x16x32_bf16 v[134:137], v[228:231], v[86:89], 0
	ds_read2_b64 v[228:231], v52 offset0:144 offset1:148
	s_waitcnt lgkmcnt(7)
	v_mov_b64_e32 v[124:125], s[86:87]
	v_mov_b64_e32 v[122:123], s[84:85]
	v_mfma_f32_16x16x32_bf16 v[86:89], v[232:235], v[86:89], 0
	ds_read2_b64 v[232:235], v53 offset0:48 offset1:52
	s_waitcnt lgkmcnt(7)
	v_readlane_b32 s85, v253, 30
	v_mfma_f32_16x16x32_bf16 v[106:109], v[236:239], v[82:85], v[126:129]
	ds_read2_b64 v[236:239], v144 offset0:88 offset1:92
	s_waitcnt lgkmcnt(7)
	v_mfma_f32_16x16x32_bf16 v[126:129], v[240:243], v[82:85], v[130:133]
	ds_read2_b64 v[240:243], v143 offset0:248 offset1:252
	s_waitcnt lgkmcnt(7)
	v_mfma_f32_16x16x32_bf16 v[130:133], v[244:247], v[82:85], v[134:137]
	ds_read2_b64 v[244:247], v52 offset0:152 offset1:156
	s_waitcnt lgkmcnt(7)
	v_mfma_f32_16x16x32_bf16 v[82:85], v[248:251], v[82:85], v[86:89]
	ds_read2_b64 v[248:251], v53 offset0:56 offset1:60
	s_waitcnt lgkmcnt(7)
	v_mfma_f32_16x16x32_bf16 v[86:89], v[220:223], v[78:81], v[106:109]
	ds_read2_b64 v[220:223], v144 offset0:96 offset1:100
	s_waitcnt lgkmcnt(7)
	v_mfma_f32_16x16x32_bf16 v[102:105], v[224:227], v[78:81], v[126:129]
	v_add_u32_e32 v50, 0x7000, v50
	ds_read2_b64 v[224:227], v50 offset1:4
	s_waitcnt lgkmcnt(7)
	v_mfma_f32_16x16x32_bf16 v[106:109], v[228:231], v[78:81], v[130:133]
	ds_read2_b64 v[228:231], v52 offset0:160 offset1:164
	s_waitcnt lgkmcnt(7)
	v_mfma_f32_16x16x32_bf16 v[126:129], v[232:235], v[78:81], v[82:85]
	ds_read2_b64 v[232:235], v53 offset0:64 offset1:68
	s_waitcnt lgkmcnt(7)
	v_mfma_f32_16x16x32_bf16 v[86:89], v[236:239], v[74:77], v[86:89]
	s_waitcnt lgkmcnt(6)
	v_mfma_f32_16x16x32_bf16 v[78:81], v[240:243], v[74:77], v[102:105]
	s_waitcnt lgkmcnt(5)
	v_mfma_f32_16x16x32_bf16 v[82:85], v[244:247], v[74:77], v[106:109]
	s_waitcnt lgkmcnt(4)
	v_mfma_f32_16x16x32_bf16 v[74:77], v[248:251], v[74:77], v[126:129]
	s_waitcnt lgkmcnt(3)
	v_mfma_f32_16x16x32_bf16 v[86:89], v[220:223], v[70:73], v[86:89]
	s_waitcnt lgkmcnt(2)
	v_mfma_f32_16x16x32_bf16 v[78:81], v[224:227], v[70:73], v[78:81]
	s_waitcnt lgkmcnt(1)
	v_mfma_f32_16x16x32_bf16 v[82:85], v[228:231], v[70:73], v[82:85]
	s_waitcnt lgkmcnt(0)
	v_mfma_f32_16x16x32_bf16 v[70:73], v[232:235], v[70:73], v[74:77]
	s_and_b64 vcc, exec, s[76:77]
